# indexer: select-loop early exit past tmax (m0 scalar) + ballot/v_writelane mask build
# baseline (speedup 1.0000x reference)
.LBB0_398:
	v_max_u32_e32 v2, 1, v66
	v_ashrrev_i32_e32 v89, 31, v88
	s_mov_b64 s[82:83], 0
	v_cmp_ge_u32_e32 vcc, v3, v2
	v_cmp_ge_u32_e64 s[74:75], v175, v2
	v_cmp_ge_u32_e64 s[100:101], v176, v2
	v_writelane_b32 v5, vcc_lo, 0
	v_writelane_b32 v6, vcc_hi, 0
	v_writelane_b32 v5, s74, 1
	v_writelane_b32 v6, s75, 1
	v_writelane_b32 v5, s100, 2
	v_writelane_b32 v6, s101, 2
	v_cmp_ge_u32_e32 vcc, v179, v2
	v_cmp_ge_u32_e64 s[74:75], v180, v2
	v_cmp_ge_u32_e64 s[100:101], v181, v2
	v_writelane_b32 v5, vcc_lo, 3
	v_writelane_b32 v6, vcc_hi, 3
	v_writelane_b32 v5, s74, 4
	v_writelane_b32 v6, s75, 4
	v_writelane_b32 v5, s100, 5
	v_writelane_b32 v6, s101, 5
	v_cmp_ge_u32_e32 vcc, v182, v2
	v_cmp_ge_u32_e64 s[74:75], v183, v2
	v_cmp_ge_u32_e64 s[100:101], v184, v2
	v_writelane_b32 v5, vcc_lo, 6
	v_writelane_b32 v6, vcc_hi, 6
	v_writelane_b32 v5, s74, 7
	v_writelane_b32 v6, s75, 7
	v_writelane_b32 v5, s100, 8
	v_writelane_b32 v6, s101, 8
	v_cmp_ge_u32_e32 vcc, v185, v2
	v_cmp_ge_u32_e64 s[74:75], v186, v2
	v_cmp_ge_u32_e64 s[100:101], v187, v2
	v_writelane_b32 v5, vcc_lo, 9
	v_writelane_b32 v6, vcc_hi, 9
	v_writelane_b32 v5, s74, 10
	v_writelane_b32 v6, s75, 10
	v_writelane_b32 v5, s100, 11
	v_writelane_b32 v6, s101, 11
	v_cmp_ge_u32_e32 vcc, v188, v2
	v_cmp_ge_u32_e64 s[74:75], v189, v2
	v_cmp_ge_u32_e64 s[100:101], v190, v2
	v_writelane_b32 v5, vcc_lo, 12
	v_writelane_b32 v6, vcc_hi, 12
	v_writelane_b32 v5, s74, 13
	v_writelane_b32 v6, s75, 13
	v_writelane_b32 v5, s100, 14
	v_writelane_b32 v6, s101, 14
	v_cmp_ge_u32_e32 vcc, v191, v2
	v_cmp_ge_u32_e64 s[74:75], v192, v2
	v_cmp_ge_u32_e64 s[100:101], v193, v2
	v_writelane_b32 v5, vcc_lo, 15
	v_writelane_b32 v6, vcc_hi, 15
	v_writelane_b32 v5, s74, 16
	v_writelane_b32 v6, s75, 16
	v_writelane_b32 v5, s100, 17
	v_writelane_b32 v6, s101, 17
	v_cmp_ge_u32_e32 vcc, v194, v2
	v_cmp_ge_u32_e64 s[74:75], v195, v2
	v_cmp_ge_u32_e64 s[100:101], v196, v2
	v_writelane_b32 v5, vcc_lo, 18
	v_writelane_b32 v6, vcc_hi, 18
	v_writelane_b32 v5, s74, 19
	v_writelane_b32 v6, s75, 19
	v_writelane_b32 v5, s100, 20
	v_writelane_b32 v6, s101, 20
	v_cmp_ge_u32_e32 vcc, v197, v2
	v_cmp_ge_u32_e64 s[74:75], v216, v2
	v_cmp_ge_u32_e64 s[100:101], v217, v2
	v_writelane_b32 v5, vcc_lo, 21
	v_writelane_b32 v6, vcc_hi, 21
	v_writelane_b32 v5, s74, 22
	v_writelane_b32 v6, s75, 22
	v_writelane_b32 v5, s100, 23
	v_writelane_b32 v6, s101, 23
	v_cmp_ge_u32_e32 vcc, v218, v2
	v_cmp_ge_u32_e64 s[74:75], v219, v2
	v_cmp_ge_u32_e64 s[100:101], v220, v2
	v_writelane_b32 v5, vcc_lo, 24
	v_writelane_b32 v6, vcc_hi, 24
	v_writelane_b32 v5, s74, 25
	v_writelane_b32 v6, s75, 25
	v_writelane_b32 v5, s100, 26
	v_writelane_b32 v6, s101, 26
	v_cmp_ge_u32_e32 vcc, v221, v2
	v_cmp_ge_u32_e64 s[74:75], v222, v2
	v_cmp_ge_u32_e64 s[100:101], v223, v2
	v_writelane_b32 v5, vcc_lo, 27
	v_writelane_b32 v6, vcc_hi, 27
	v_writelane_b32 v5, s74, 28
	v_writelane_b32 v6, s75, 28
	v_writelane_b32 v5, s100, 29
	v_writelane_b32 v6, s101, 29
	v_cmp_ge_u32_e32 vcc, v224, v2
	v_cmp_ge_u32_e64 s[74:75], v225, v2
	v_cmp_ge_u32_e64 s[100:101], v226, v2
	v_writelane_b32 v5, vcc_lo, 30
	v_writelane_b32 v6, vcc_hi, 30
	v_writelane_b32 v5, s74, 31
	v_writelane_b32 v6, s75, 31
	v_writelane_b32 v5, s100, 32
	v_writelane_b32 v6, s101, 32
	v_cmp_ge_u32_e32 vcc, v227, v2
	v_cmp_ge_u32_e64 s[74:75], v228, v2
	v_cmp_ge_u32_e64 s[100:101], v229, v2
	v_writelane_b32 v5, vcc_lo, 33
	v_writelane_b32 v6, vcc_hi, 33
	v_writelane_b32 v5, s74, 34
	v_writelane_b32 v6, s75, 34
	v_writelane_b32 v5, s100, 35
	v_writelane_b32 v6, s101, 35
	v_cmp_ge_u32_e32 vcc, v230, v2
	v_cmp_ge_u32_e64 s[74:75], v231, v2
	v_cmp_ge_u32_e64 s[100:101], v232, v2
	v_writelane_b32 v5, vcc_lo, 36
	v_writelane_b32 v6, vcc_hi, 36
	v_writelane_b32 v5, s74, 37
	v_writelane_b32 v6, s75, 37
	v_writelane_b32 v5, s100, 38
	v_writelane_b32 v6, s101, 38
	v_cmp_ge_u32_e32 vcc, v233, v2
	v_cmp_ge_u32_e64 s[74:75], v234, v2
	v_cmp_ge_u32_e64 s[100:101], v235, v2
	v_writelane_b32 v5, vcc_lo, 39
	v_writelane_b32 v6, vcc_hi, 39
	v_writelane_b32 v5, s74, 40
	v_writelane_b32 v6, s75, 40
	v_writelane_b32 v5, s100, 41
	v_writelane_b32 v6, s101, 41
	v_cmp_ge_u32_e32 vcc, v236, v2
	v_cmp_ge_u32_e64 s[74:75], v237, v2
	v_cmp_ge_u32_e64 s[100:101], v238, v2
	v_writelane_b32 v5, vcc_lo, 42
	v_writelane_b32 v6, vcc_hi, 42
	v_writelane_b32 v5, s74, 43
	v_writelane_b32 v6, s75, 43
	v_writelane_b32 v5, s100, 44
	v_writelane_b32 v6, s101, 44
	v_cmp_ge_u32_e32 vcc, v239, v2
	v_cmp_ge_u32_e64 s[74:75], v240, v2
	v_cmp_ge_u32_e64 s[100:101], v241, v2
	v_writelane_b32 v5, vcc_lo, 45
	v_writelane_b32 v6, vcc_hi, 45
	v_writelane_b32 v5, s74, 46
	v_writelane_b32 v6, s75, 46
	v_writelane_b32 v5, s100, 47
	v_writelane_b32 v6, s101, 47
	v_cmp_ge_u32_e32 vcc, v242, v2
	v_cmp_ge_u32_e64 s[74:75], v243, v2
	v_cmp_ge_u32_e64 s[100:101], v244, v2
	v_writelane_b32 v5, vcc_lo, 48
	v_writelane_b32 v6, vcc_hi, 48
	v_writelane_b32 v5, s74, 49
	v_writelane_b32 v6, s75, 49
	v_writelane_b32 v5, s100, 50
	v_writelane_b32 v6, s101, 50
	v_cmp_ge_u32_e32 vcc, v245, v2
	v_cmp_ge_u32_e64 s[74:75], v246, v2
	v_cmp_ge_u32_e64 s[100:101], v247, v2
	v_writelane_b32 v5, vcc_lo, 51
	v_writelane_b32 v6, vcc_hi, 51
	v_writelane_b32 v5, s74, 52
	v_writelane_b32 v6, s75, 52
	v_writelane_b32 v5, s100, 53
	v_writelane_b32 v6, s101, 53
	v_cmp_ge_u32_e32 vcc, v248, v2
	v_cmp_ge_u32_e64 s[74:75], v249, v2
	v_cmp_ge_u32_e64 s[100:101], v250, v2
	v_writelane_b32 v5, vcc_lo, 54
	v_writelane_b32 v6, vcc_hi, 54
	v_writelane_b32 v5, s74, 55
	v_writelane_b32 v6, s75, 55
	v_writelane_b32 v5, s100, 56
	v_writelane_b32 v6, s101, 56
	v_cmp_ge_u32_e32 vcc, v199, v2
	v_cmp_ge_u32_e64 s[74:75], v200, v2
	v_cmp_ge_u32_e64 s[100:101], v207, v2
	v_writelane_b32 v5, vcc_lo, 57
	v_writelane_b32 v6, vcc_hi, 57
	v_writelane_b32 v5, s74, 58
	v_writelane_b32 v6, s75, 58
	v_writelane_b32 v5, s100, 59
	v_writelane_b32 v6, s101, 59
	v_cmp_ge_u32_e32 vcc, v208, v2
	v_cmp_ge_u32_e64 s[74:75], v210, v2
	v_cmp_ge_u32_e64 s[100:101], v70, v2
	v_writelane_b32 v5, vcc_lo, 60
	v_writelane_b32 v6, vcc_hi, 60
	v_writelane_b32 v5, s74, 61
	v_writelane_b32 v6, s75, 61
	v_writelane_b32 v5, s100, 62
	v_writelane_b32 v6, s101, 62
	v_cmp_ge_u32_e32 vcc, v18, v2
	s_nop 1
	v_writelane_b32 v5, vcc_lo, 63
	v_writelane_b32 v6, vcc_hi, 63
	v_mov_b32_e32 v2, v5
	v_lshlrev_b64 v[4:5], 8, v[88:89]
	v_lshl_add_u64 v[4:5], v[84:85], 0, v[4:5]
	global_store_dword v[4:5], v2, off
	v_or_b32_e32 v2, 1, v88
	v_ashrrev_i32_e32 v3, 31, v2
	v_lshlrev_b64 v[2:3], 8, v[2:3]
	v_lshl_add_u64 v[2:3], v[84:85], 0, v[2:3]
	s_and_b64 vcc, exec, s[80:81]
	global_store_dword v[2:3], v6, off
	s_cbranch_vccnz .LBB0_396

.LBB0_651:
	s_or_b64 exec, exec, s[82:83]
	v_max_f32_e32 v2, v2, v2
	v_max_f32_e32 v2, 0, v2
	v_max_f32_e32 v3, v3, v3
	v_fma_f32 v2, v174, v2, 0
	v_max_f32_e32 v3, 0, v3
	v_fmac_f32_e32 v2, v173, v3
	v_max_f32_e32 v3, v4, v4
	v_max_f32_e32 v3, 0, v3
	v_fmac_f32_e32 v2, v172, v3
	v_max_f32_e32 v3, v5, v5
	v_max_f32_e32 v3, 0, v3
	v_fmac_f32_e32 v2, v171, v3
	v_max_f32_e32 v3, v6, v6
	v_max_f32_e32 v3, 0, v3
	v_fmac_f32_e32 v2, v170, v3
	v_max_f32_e32 v3, v7, v7
	v_max_f32_e32 v3, 0, v3
	v_fmac_f32_e32 v2, v169, v3
	v_max_f32_e32 v3, v8, v8
	v_max_f32_e32 v3, 0, v3
	v_fmac_f32_e32 v2, v168, v3
	v_max_f32_e32 v3, v9, v9
	v_max_f32_e32 v3, 0, v3
	v_fmac_f32_e32 v2, v167, v3
	v_max_f32_e32 v3, v10, v10
	v_max_f32_e32 v3, 0, v3
	v_fmac_f32_e32 v2, v166, v3
	v_max_f32_e32 v3, v11, v11
	v_max_f32_e32 v3, 0, v3
	v_fmac_f32_e32 v2, v165, v3
	v_max_f32_e32 v3, v12, v12
	v_max_f32_e32 v3, 0, v3
	v_fmac_f32_e32 v2, v164, v3
	v_max_f32_e32 v3, v13, v13
	v_max_f32_e32 v3, 0, v3
	v_fmac_f32_e32 v2, v163, v3
	v_max_f32_e32 v3, v14, v14
	v_max_f32_e32 v3, 0, v3
	v_fmac_f32_e32 v2, v162, v3
	v_max_f32_e32 v3, v15, v15
	v_max_f32_e32 v3, 0, v3
	v_fmac_f32_e32 v2, v161, v3
	v_max_f32_e32 v3, v16, v16
	v_max_f32_e32 v3, 0, v3
	v_fmac_f32_e32 v2, v160, v3
	v_max_f32_e32 v3, v17, v17
	v_max_f32_e32 v3, 0, v3
	v_fmac_f32_e32 v2, v89, v3
	v_not_b32_e32 v3, v2
	v_or_b32_e32 v4, 0x80000000, v2
	v_cmp_gt_i32_e32 vcc, 0, v2
	s_nop 1
	v_cndmask_b32_e32 v2, v4, v3, vcc
	v_cmp_le_u32_e32 vcc, v93, v87
	s_nop 1
	v_cndmask_b32_e32 v3, 0, v2, vcc
	v_mov_b32_e32 v2, 31
	v_readfirstlane_b32 s100, v177
	s_nop 1
	s_add_i32 s100, s100, 1
	s_lshr_b32 m0, s100, 5
	s_branch .LBB0_654
.LBB0_652:
	v_lshlrev_b32_e64 v5, v2, 1
	v_or_b32_e32 v5, v66, v5
	v_add_u32_e32 v2, -1, v2
	v_mov_b32_e32 v6, 0
	v_mov_b32_e32 v7, 0
	v_mov_b32_e32 v8, 0
	v_cmp_ge_u32_e32 vcc, v3, v5
	v_cmp_ge_u32_e64 s[82:83], v175, v5
	v_cmp_ge_u32_e64 s[100:101], v176, v5
	v_addc_co_u32_e32 v6, vcc, 0, v6, vcc
	v_addc_co_u32_e64 v7, s[82:83], 0, v7, s[82:83]
	v_addc_co_u32_e64 v8, s[100:101], 0, v8, s[100:101]
	v_cmp_ge_u32_e32 vcc, v179, v5
	v_cmp_ge_u32_e64 s[82:83], v180, v5
	v_cmp_ge_u32_e64 s[100:101], v181, v5
	v_addc_co_u32_e32 v6, vcc, 0, v6, vcc
	v_addc_co_u32_e64 v7, s[82:83], 0, v7, s[82:83]
	v_addc_co_u32_e64 v8, s[100:101], 0, v8, s[100:101]
	v_cmp_ge_u32_e32 vcc, v182, v5
	v_cmp_ge_u32_e64 s[82:83], v183, v5
	v_cmp_ge_u32_e64 s[100:101], v184, v5
	v_addc_co_u32_e32 v6, vcc, 0, v6, vcc
	v_addc_co_u32_e64 v7, s[82:83], 0, v7, s[82:83]
	v_addc_co_u32_e64 v8, s[100:101], 0, v8, s[100:101]
	s_cmp_lt_u32 m0, 9
	s_cbranch_scc1 .Lidxsel_sum
	v_cmp_ge_u32_e32 vcc, v185, v5
	v_cmp_ge_u32_e64 s[82:83], v186, v5
	v_cmp_ge_u32_e64 s[100:101], v187, v5
	v_addc_co_u32_e32 v6, vcc, 0, v6, vcc
	v_addc_co_u32_e64 v7, s[82:83], 0, v7, s[82:83]
	v_addc_co_u32_e64 v8, s[100:101], 0, v8, s[100:101]
	v_cmp_ge_u32_e32 vcc, v188, v5
	v_cmp_ge_u32_e64 s[82:83], v189, v5
	v_cmp_ge_u32_e64 s[100:101], v190, v5
	v_addc_co_u32_e32 v6, vcc, 0, v6, vcc
	v_addc_co_u32_e64 v7, s[82:83], 0, v7, s[82:83]
	v_addc_co_u32_e64 v8, s[100:101], 0, v8, s[100:101]
	v_cmp_ge_u32_e32 vcc, v191, v5
	v_cmp_ge_u32_e64 s[82:83], v192, v5
	v_cmp_ge_u32_e64 s[100:101], v193, v5
	v_addc_co_u32_e32 v6, vcc, 0, v6, vcc
	v_addc_co_u32_e64 v7, s[82:83], 0, v7, s[82:83]
	v_addc_co_u32_e64 v8, s[100:101], 0, v8, s[100:101]
	s_cmp_lt_u32 m0, 18
	s_cbranch_scc1 .Lidxsel_sum
	v_cmp_ge_u32_e32 vcc, v194, v5
	v_cmp_ge_u32_e64 s[82:83], v195, v5
	v_cmp_ge_u32_e64 s[100:101], v196, v5
	v_addc_co_u32_e32 v6, vcc, 0, v6, vcc
	v_addc_co_u32_e64 v7, s[82:83], 0, v7, s[82:83]
	v_addc_co_u32_e64 v8, s[100:101], 0, v8, s[100:101]
	v_cmp_ge_u32_e32 vcc, v197, v5
	v_cmp_ge_u32_e64 s[82:83], v216, v5
	v_cmp_ge_u32_e64 s[100:101], v217, v5
	v_addc_co_u32_e32 v6, vcc, 0, v6, vcc
	v_addc_co_u32_e64 v7, s[82:83], 0, v7, s[82:83]
	v_addc_co_u32_e64 v8, s[100:101], 0, v8, s[100:101]
	v_cmp_ge_u32_e32 vcc, v218, v5
	v_cmp_ge_u32_e64 s[82:83], v219, v5
	v_cmp_ge_u32_e64 s[100:101], v220, v5
	v_addc_co_u32_e32 v6, vcc, 0, v6, vcc
	v_addc_co_u32_e64 v7, s[82:83], 0, v7, s[82:83]
	v_addc_co_u32_e64 v8, s[100:101], 0, v8, s[100:101]
	s_cmp_lt_u32 m0, 27
	s_cbranch_scc1 .Lidxsel_sum
	v_cmp_ge_u32_e32 vcc, v221, v5
	v_cmp_ge_u32_e64 s[82:83], v222, v5
	v_cmp_ge_u32_e64 s[100:101], v223, v5
	v_addc_co_u32_e32 v6, vcc, 0, v6, vcc
	v_addc_co_u32_e64 v7, s[82:83], 0, v7, s[82:83]
	v_addc_co_u32_e64 v8, s[100:101], 0, v8, s[100:101]
	v_cmp_ge_u32_e32 vcc, v224, v5
	v_cmp_ge_u32_e64 s[82:83], v225, v5
	v_cmp_ge_u32_e64 s[100:101], v226, v5
	v_addc_co_u32_e32 v6, vcc, 0, v6, vcc
	v_addc_co_u32_e64 v7, s[82:83], 0, v7, s[82:83]
	v_addc_co_u32_e64 v8, s[100:101], 0, v8, s[100:101]
	v_cmp_ge_u32_e32 vcc, v227, v5
	v_cmp_ge_u32_e64 s[82:83], v228, v5
	v_cmp_ge_u32_e64 s[100:101], v229, v5
	v_addc_co_u32_e32 v6, vcc, 0, v6, vcc
	v_addc_co_u32_e64 v7, s[82:83], 0, v7, s[82:83]
	v_addc_co_u32_e64 v8, s[100:101], 0, v8, s[100:101]
	s_cmp_lt_u32 m0, 36
	s_cbranch_scc1 .Lidxsel_sum
	v_cmp_ge_u32_e32 vcc, v230, v5
	v_cmp_ge_u32_e64 s[82:83], v231, v5
	v_cmp_ge_u32_e64 s[100:101], v232, v5
	v_addc_co_u32_e32 v6, vcc, 0, v6, vcc
	v_addc_co_u32_e64 v7, s[82:83], 0, v7, s[82:83]
	v_addc_co_u32_e64 v8, s[100:101], 0, v8, s[100:101]
	v_cmp_ge_u32_e32 vcc, v233, v5
	v_cmp_ge_u32_e64 s[82:83], v234, v5
	v_cmp_ge_u32_e64 s[100:101], v235, v5
	v_addc_co_u32_e32 v6, vcc, 0, v6, vcc
	v_addc_co_u32_e64 v7, s[82:83], 0, v7, s[82:83]
	v_addc_co_u32_e64 v8, s[100:101], 0, v8, s[100:101]
	v_cmp_ge_u32_e32 vcc, v236, v5
	v_cmp_ge_u32_e64 s[82:83], v237, v5
	v_cmp_ge_u32_e64 s[100:101], v238, v5
	v_addc_co_u32_e32 v6, vcc, 0, v6, vcc
	v_addc_co_u32_e64 v7, s[82:83], 0, v7, s[82:83]
	v_addc_co_u32_e64 v8, s[100:101], 0, v8, s[100:101]
	s_cmp_lt_u32 m0, 45
	s_cbranch_scc1 .Lidxsel_sum
	v_cmp_ge_u32_e32 vcc, v239, v5
	v_cmp_ge_u32_e64 s[82:83], v240, v5
	v_cmp_ge_u32_e64 s[100:101], v241, v5
	v_addc_co_u32_e32 v6, vcc, 0, v6, vcc
	v_addc_co_u32_e64 v7, s[82:83], 0, v7, s[82:83]
	v_addc_co_u32_e64 v8, s[100:101], 0, v8, s[100:101]
	v_cmp_ge_u32_e32 vcc, v242, v5
	v_cmp_ge_u32_e64 s[82:83], v243, v5
	v_cmp_ge_u32_e64 s[100:101], v244, v5
	v_addc_co_u32_e32 v6, vcc, 0, v6, vcc
	v_addc_co_u32_e64 v7, s[82:83], 0, v7, s[82:83]
	v_addc_co_u32_e64 v8, s[100:101], 0, v8, s[100:101]
	v_cmp_ge_u32_e32 vcc, v245, v5
	v_cmp_ge_u32_e64 s[82:83], v246, v5
	v_cmp_ge_u32_e64 s[100:101], v247, v5
	v_addc_co_u32_e32 v6, vcc, 0, v6, vcc
	v_addc_co_u32_e64 v7, s[82:83], 0, v7, s[82:83]
	v_addc_co_u32_e64 v8, s[100:101], 0, v8, s[100:101]
	s_cmp_lt_u32 m0, 54
	s_cbranch_scc1 .Lidxsel_sum
	v_cmp_ge_u32_e32 vcc, v248, v5
	v_cmp_ge_u32_e64 s[82:83], v249, v5
	v_cmp_ge_u32_e64 s[100:101], v250, v5
	v_addc_co_u32_e32 v6, vcc, 0, v6, vcc
	v_addc_co_u32_e64 v7, s[82:83], 0, v7, s[82:83]
	v_addc_co_u32_e64 v8, s[100:101], 0, v8, s[100:101]
	v_cmp_ge_u32_e32 vcc, v199, v5
	v_cmp_ge_u32_e64 s[82:83], v200, v5
	v_cmp_ge_u32_e64 s[100:101], v207, v5
	v_addc_co_u32_e32 v6, vcc, 0, v6, vcc
	v_addc_co_u32_e64 v7, s[82:83], 0, v7, s[82:83]
	v_addc_co_u32_e64 v8, s[100:101], 0, v8, s[100:101]
	v_cmp_ge_u32_e32 vcc, v208, v5
	v_cmp_ge_u32_e64 s[82:83], v210, v5
	v_cmp_ge_u32_e64 s[100:101], v70, v5
	v_addc_co_u32_e32 v6, vcc, 0, v6, vcc
	v_addc_co_u32_e64 v7, s[82:83], 0, v7, s[82:83]
	v_addc_co_u32_e64 v8, s[100:101], 0, v8, s[100:101]
	v_cmp_ge_u32_e32 vcc, v18, v5
	s_nop 1
	v_addc_co_u32_e32 v6, vcc, 0, v6, vcc
.Lidxsel_sum:
	v_add3_u32 v6, v6, v7, v8
	s_nop 1
	v_add_u32_dpp v6, v6, v6 quad_perm:[1,0,3,2] row_mask:0xf bank_mask:0xf
	s_nop 1
	v_add_u32_dpp v6, v6, v6 quad_perm:[2,3,0,1] row_mask:0xf bank_mask:0xf
	s_nop 1
	v_add_u32_dpp v6, v6, v6 row_ror:4 row_mask:0xf bank_mask:0xf
	s_nop 1
	v_add_u32_dpp v6, v6, v6 row_ror:8 row_mask:0xf bank_mask:0xf
	ds_swizzle_b32 v7, v6 offset:swizzle(SWAP,16)
	s_waitcnt lgkmcnt(0)
	v_add_u32_e32 v6, v6, v7
	v_cmp_gt_i32_e32 vcc, s33, v6
	s_or_b64 vcc, s[74:75], vcc
	v_cmp_eq_u32_e64 s[74:75], s33, v6
	v_cndmask_b32_e32 v66, v5, v66, vcc
	s_nop 0
	v_cndmask_b32_e64 v5, 0, 1, s[74:75]
	v_cndmask_b32_e32 v4, v5, v4, vcc
	v_and_b32_e32 v4, 1, v4
	v_cmp_eq_u32_e64 s[82:83], 1, v4
	v_cmp_eq_u32_e32 vcc, -1, v2
